# hand-written per-row phase (stats, GQA q/k rmsnorm+axial rope, v copy, MLA k_rope): 16B/lane loads+stores, DPP reductions/partner exchange, next-row prefetch
# speedup vs baseline: 1.0253x; 1.0253x over previous
.Lrw_entry:
	v_ashrrev_i32_e32 v9, 6, v84
	v_and_b32_e32 v10, 63, v84
	v_and_b32_e32 v8, 31, v84
	s_waitcnt vmcnt(0)
	s_mov_b64 s[20:21], exec
	s_mov_b32 s22, -1
	s_mov_b32 s23, 0xffff
	s_mov_b32 s26, 0
	s_mov_b32 s27, 0xffff0000
	s_mov_b32 s76, 0xffff
	s_mov_b32 s77, 0
	s_mov_b32 s78, 0xffffff
	s_mov_b32 s79, 0
	s_mov_b32 s80, 1
	s_mov_b32 s81, 0
	s_mov_b32 s6, 0
	s_cmp_lg_u64 s[90:91], 0
	s_cselect_b32 s6, 1, 0
	s_add_u32 s82, s50, 0x1076000
	s_addc_u32 s83, s51, 0
	s_add_u32 s98, s50, 0x1079000
	s_addc_u32 s99, s51, 0
	v_and_b32_e32 v160, 63, v143
	v_lshrrev_b32_e32 v161, 3, v160
	v_and_b32_e32 v162, 7, v160
	v_lshlrev_b32_e32 v163, 4, v162
	v_cmp_gt_u32_e64 s[100:101], 4, v162
	v_cmp_gt_u32_e32 vcc, 6, v161
	v_lshl_add_u32 v196, v161, 7, v163
	v_mov_b32_e32 v164, 64
	v_mov_b32_e32 v165, 0x540
	v_cndmask_b32_e32 v164, v164, v165, vcc
	v_add_u32_e32 v196, v196, v164
	s_mov_b32 s0, 557056
	v_mul_lo_u32 v197, s0, v161
	v_add_u32_e32 v197, v197, v163
	v_mov_b32_e32 v164, 0x1852d000
	v_mov_b32_e32 v165, 0x16edd000
	v_cndmask_b32_e32 v164, v164, v165, vcc
	v_add_u32_e32 v197, v197, v164
	v_mov_b32_e32 v164, 1114112
	v_mov_b32_e32 v165, 3342336
	v_cndmask_b32_e32 v198, v164, v165, vcc
	v_mov_b32_e32 v164, 1.0
	v_mov_b32_e32 v165, 0x3e38aa3b
	v_cndmask_b32_e32 v209, v164, v165, vcc
	v_and_b32_e32 v164, 2, v162
	v_cmp_eq_u32_e32 vcc, 0, v164
	v_mov_b32_e32 v164, 1.0
	v_mov_b32_e32 v165, -1.0
	v_cndmask_b32_e32 v207, v164, v165, vcc
	v_and_b32_e32 v164, 1, v162
	v_lshlrev_b32_e32 v205, 5, v164
	v_add_u32_e32 v205, 0x1000, v205
	v_lshlrev_b32_e32 v199, 4, v160
	v_add_u32_e32 v200, 0x440, v199
	v_lshrrev_b32_e32 v164, 3, v160
	v_mul_lo_u32 v201, s0, v164
	v_add_u32_e32 v201, v201, v163
	v_add_u32_e32 v201, 0x190dd000, v201
	v_mov_b32_e32 v216, 1114112
	v_and_b32_e32 v164, 3, v160
	v_lshlrev_b32_e32 v165, 4, v164
	v_add_u32_e32 v202, 0x300, v165
	v_lshrrev_b32_e32 v166, 2, v160
	s_mov_b32 s1, 835584
	v_mul_lo_u32 v203, s1, v166
	v_add_u32_e32 v203, v203, v165
	v_add_u32_e32 v203, 0x12f1d080, v203
	v_mov_b32_e32 v204, 5013504
	v_cmp_lt_u32_e64 s[70:71], 1, v164
	v_and_b32_e32 v166, 1, v164
	v_cmp_eq_u32_e32 vcc, 0, v166
	v_mov_b32_e32 v166, 1.0
	v_mov_b32_e32 v167, -1.0
	v_cndmask_b32_e32 v208, v166, v167, vcc
	s_lshl_b32 s0, s74, 8
	v_lshlrev_b32_e32 v164, 5, v162
	v_add_u32_e32 v164, s0, v164
	v_readlane_b32 s8, v253, 26
	v_readlane_b32 s9, v253, 27
	s_nop 4
	s_mov_b64 exec, s[22:23]
	global_load_dwordx4 v[188:191], v164, s[8:9]
	global_load_dwordx4 v[192:195], v164, s[8:9] offset:16
	s_mov_b64 exec, s[20:21]
	v_readlane_b32 s8, v253, 28
	v_readlane_b32 s9, v253, 29
	s_nop 4
	s_mov_b64 exec, s[26:27]
	global_load_dwordx4 v[188:191], v164, s[8:9]
	global_load_dwordx4 v[192:195], v164, s[8:9] offset:16
	s_mov_b64 exec, s[20:21]
	v_readfirstlane_b32 s0, v143
	s_lshr_b32 s0, s0, 6
	v_readlane_b32 s4, v253, 0
	s_lshl_b32 s4, s4, 3
	s_add_i32 s4, s4, s0
	v_readlane_b32 s5, v255, 23
	s_lshl_b32 s5, s5, 3
	s_waitcnt vmcnt(0)
	s_cmp_ge_u32 s4, 34816
	s_cbranch_scc1 .Lrw_done
	s_mul_i32 s0, s4, 5184
	s_add_u32 s0, s0, 0x5cbd000
	s_add_u32 s10, s50, s0
	s_addc_u32 s11, s51, 0
	s_and_b32 s1, s4, 0xfff
	s_lshr_b32 s7, s1, 6
	s_and_b32 s19, s1, 63
	global_load_dwordx4 v[0:3], v196, s[10:11]
	global_load_dwordx4 v[4:7], v199, s[10:11]
	global_load_dwordx4 v[12:15], v200, s[10:11]
	global_load_dwordx4 v[16:19], v202, s[10:11]
	v_mov_b32_e32 v212, s19
	v_mov_b32_e32 v213, s7
	v_cndmask_b32_e64 v212, v212, v213, s[100:101]
	v_lshl_add_u32 v212, v212, 6, v205
	v_add_u32_e32 v213, 0x1000, v212
	global_load_dwordx4 v[20:23], v212, s[82:83]
	global_load_dwordx4 v[24:27], v212, s[82:83] offset:16
	global_load_dwordx4 v[28:31], v213, s[82:83]
	global_load_dwordx4 v[32:35], v213, s[82:83] offset:16
	v_mov_b32_e32 v212, s7
	v_mov_b32_e32 v213, s19
	v_cndmask_b32_e64 v212, v212, v213, s[70:71]
	v_lshlrev_b32_e32 v212, 5, v212
	global_load_dwordx4 v[36:39], v212, s[82:83]
	global_load_dwordx4 v[40:43], v212, s[82:83] offset:16
	global_load_dwordx4 v[44:47], v212, s[82:83] offset:2048
	global_load_dwordx4 v[48:51], v212, s[82:83] offset:2064
	global_load_dword v217, v199, s[10:11]
	global_load_dword v218, v199, s[10:11]
	global_load_dword v219, v199, s[10:11]
	global_load_dword v220, v199, s[10:11]
.Lrw_loop:
	s_add_u32 s18, s4, s5
	s_min_u32 s17, s18, 34815
	s_mul_i32 s0, s17, 5184
	s_add_u32 s0, s0, 0x5cbd000
	s_add_u32 s10, s50, s0
	s_addc_u32 s11, s51, 0
	s_and_b32 s1, s17, 0xfff
	s_lshr_b32 s7, s1, 6
	s_and_b32 s19, s1, 63
	global_load_dwordx4 v[52:55], v196, s[10:11]
	global_load_dwordx4 v[56:59], v199, s[10:11]
	global_load_dwordx4 v[60:63], v200, s[10:11]
	global_load_dwordx4 v[64:67], v202, s[10:11]
	v_mov_b32_e32 v212, s19
	v_mov_b32_e32 v213, s7
	v_cndmask_b32_e64 v212, v212, v213, s[100:101]
	v_lshl_add_u32 v212, v212, 6, v205
	v_add_u32_e32 v213, 0x1000, v212
	global_load_dwordx4 v[96:99], v212, s[82:83]
	global_load_dwordx4 v[100:103], v212, s[82:83] offset:16
	global_load_dwordx4 v[104:107], v213, s[82:83]
	global_load_dwordx4 v[108:111], v213, s[82:83] offset:16
	v_mov_b32_e32 v212, s7
	v_mov_b32_e32 v213, s19
	v_cndmask_b32_e64 v212, v212, v213, s[70:71]
	v_lshlrev_b32_e32 v212, 5, v212
	global_load_dwordx4 v[112:115], v212, s[82:83]
	global_load_dwordx4 v[116:119], v212, s[82:83] offset:16
	global_load_dwordx4 v[120:123], v212, s[82:83] offset:2048
	global_load_dwordx4 v[124:127], v212, s[82:83] offset:2064
	s_lshr_b32 s12, s4, 12
	s_and_b32 s13, s4, 0xfff
	s_mov_b32 s14, 1
	s_cmp_lt_u32 s4, 0x8000
	s_cbranch_scc1 .Lrw_r0_lat
	s_sub_i32 s12, s4, 0x8000
	s_and_b32 s13, s12, 0xff
	s_add_i32 s13, s13, 0x1000
	s_lshr_b32 s12, s12, 8
	s_mov_b32 s14, 0
.Lrw_r0_lat:
	s_waitcnt vmcnt(16)
	v_lshlrev_b32_e32 v144, 16, v4
	v_and_b32_e32 v145, 0xffff0000, v4
	v_lshlrev_b32_e32 v146, 16, v5
	v_and_b32_e32 v147, 0xffff0000, v5
	v_lshlrev_b32_e32 v148, 16, v6
	v_and_b32_e32 v149, 0xffff0000, v6
	v_lshlrev_b32_e32 v150, 16, v7
	v_and_b32_e32 v151, 0xffff0000, v7
	v_mul_f32_e32 v160, v144, v144
	v_fmac_f32_e32 v160, v145, v145
	v_fmac_f32_e32 v160, v146, v146
	v_fmac_f32_e32 v160, v147, v147
	v_fmac_f32_e32 v160, v148, v148
	v_fmac_f32_e32 v160, v149, v149
	v_fmac_f32_e32 v160, v150, v150
	v_fmac_f32_e32 v160, v151, v151
	s_nop 1
	v_add_f32_dpp v160, v160, v160 quad_perm:[1,0,3,2] row_mask:0xf bank_mask:0xf
	s_nop 1
	v_add_f32_dpp v160, v160, v160 quad_perm:[2,3,0,1] row_mask:0xf bank_mask:0xf
	s_nop 1
	v_add_f32_dpp v160, v160, v160 row_half_mirror row_mask:0xf bank_mask:0xf
	s_nop 1
	v_add_f32_dpp v160, v160, v160 row_mirror row_mask:0xf bank_mask:0xf
	s_nop 1
	v_readlane_b32 s0, v160, 0
	v_readlane_b32 s1, v160, 16
	v_readlane_b32 s7, v160, 32
	v_mov_b32_e32 v161, s0
	v_add_f32_e32 v161, s1, v161
	v_mov_b32_e32 v162, 0x358637bd
	v_fmamk_f32 v161, v161, 0x3b800000, v162
	v_mov_b32_e32 v163, s7
	v_fmamk_f32 v163, v163, 0x3c000000, v162
	v_rsq_f32_e32 v214, v161
	v_rsq_f32_e32 v215, v163
	s_lshl_b32 s0, s4, 3
	v_mov_b32_e32 v164, s0
	s_mov_b64 exec, s[80:81]
	global_store_dwordx2 v164, v[214:215], s[98:99]
	s_mov_b64 exec, s[20:21]
	v_mul_lo_u32 v160, s12, v216
	s_lshl_b32 s0, s13, 7
	v_add3_u32 v160, v160, v201, s0
	s_mov_b64 exec, s[76:77]
	global_store_dwordx4 v160, v[12:15], s[50:51]
	s_mov_b64 exec, s[20:21]
	v_lshlrev_b32_e32 v144, 16, v0
	v_and_b32_e32 v145, 0xffff0000, v0
	v_lshlrev_b32_e32 v146, 16, v1
	v_and_b32_e32 v147, 0xffff0000, v1
	v_lshlrev_b32_e32 v148, 16, v2
	v_and_b32_e32 v149, 0xffff0000, v2
	v_lshlrev_b32_e32 v150, 16, v3
	v_and_b32_e32 v151, 0xffff0000, v3
	v_mul_f32_e32 v160, v144, v144
	v_fmac_f32_e32 v160, v145, v145
	v_fmac_f32_e32 v160, v146, v146
	v_fmac_f32_e32 v160, v147, v147
	v_fmac_f32_e32 v160, v148, v148
	v_fmac_f32_e32 v160, v149, v149
	v_fmac_f32_e32 v160, v150, v150
	v_fmac_f32_e32 v160, v151, v151
	s_nop 1
	v_add_f32_dpp v160, v160, v160 quad_perm:[1,0,3,2] row_mask:0xf bank_mask:0xf
	s_nop 1
	v_add_f32_dpp v160, v160, v160 quad_perm:[2,3,0,1] row_mask:0xf bank_mask:0xf
	s_nop 1
	v_add_f32_dpp v160, v160, v160 row_half_mirror row_mask:0xf bank_mask:0xf
	v_mov_b32_e32 v162, 0x358637bd
	v_fmamk_f32 v160, v160, 0x3c800000, v162
	v_rsq_f32_e32 v160, v160
	s_nop 0
	v_mul_f32_e32 v144, v144, v160
	v_mul_f32_e32 v144, v144, v188
	v_mul_f32_e32 v145, v145, v160
	v_mul_f32_e32 v145, v145, v189
	v_mul_f32_e32 v146, v146, v160
	v_mul_f32_e32 v146, v146, v190
	v_mul_f32_e32 v147, v147, v160
	v_mul_f32_e32 v147, v147, v191
	v_mul_f32_e32 v148, v148, v160
	v_mul_f32_e32 v148, v148, v192
	v_mul_f32_e32 v149, v149, v160
	v_mul_f32_e32 v149, v149, v193
	v_mul_f32_e32 v150, v150, v160
	v_mul_f32_e32 v150, v150, v194
	v_mul_f32_e32 v151, v151, v160
	v_mul_f32_e32 v151, v151, v195
	s_cmp_eq_u32 s14, 0
	s_cbranch_scc1 .Lrw_r0_norope
	s_nop 0
	v_mov_b32_dpp v152, v144 quad_perm:[2,3,0,1] row_mask:0xf bank_mask:0xf
	v_mov_b32_dpp v153, v145 quad_perm:[2,3,0,1] row_mask:0xf bank_mask:0xf
	v_mov_b32_dpp v154, v146 quad_perm:[2,3,0,1] row_mask:0xf bank_mask:0xf
	v_mov_b32_dpp v155, v147 quad_perm:[2,3,0,1] row_mask:0xf bank_mask:0xf
	v_mov_b32_dpp v156, v148 quad_perm:[2,3,0,1] row_mask:0xf bank_mask:0xf
	v_mov_b32_dpp v157, v149 quad_perm:[2,3,0,1] row_mask:0xf bank_mask:0xf
	v_mov_b32_dpp v158, v150 quad_perm:[2,3,0,1] row_mask:0xf bank_mask:0xf
	v_mov_b32_dpp v159, v151 quad_perm:[2,3,0,1] row_mask:0xf bank_mask:0xf
	v_mul_f32_e32 v152, v152, v28
	v_mul_f32_e32 v144, v144, v20
	v_fmac_f32_e32 v144, v152, v207
	v_mul_f32_e32 v153, v153, v29
	v_mul_f32_e32 v145, v145, v21
	v_fmac_f32_e32 v145, v153, v207
	v_mul_f32_e32 v154, v154, v30
	v_mul_f32_e32 v146, v146, v22
	v_fmac_f32_e32 v146, v154, v207
	v_mul_f32_e32 v155, v155, v31
	v_mul_f32_e32 v147, v147, v23
	v_fmac_f32_e32 v147, v155, v207
	v_mul_f32_e32 v156, v156, v32
	v_mul_f32_e32 v148, v148, v24
	v_fmac_f32_e32 v148, v156, v207
	v_mul_f32_e32 v157, v157, v33
	v_mul_f32_e32 v149, v149, v25
	v_fmac_f32_e32 v149, v157, v207
	v_mul_f32_e32 v158, v158, v34
	v_mul_f32_e32 v150, v150, v26
	v_fmac_f32_e32 v150, v158, v207
	v_mul_f32_e32 v159, v159, v35
	v_mul_f32_e32 v151, v151, v27
	v_fmac_f32_e32 v151, v159, v207
.Lrw_r0_norope:
	v_mul_f32_e32 v144, v144, v209
	v_mul_f32_e32 v145, v145, v209
	v_mul_f32_e32 v146, v146, v209
	v_mul_f32_e32 v147, v147, v209
	v_mul_f32_e32 v148, v148, v209
	v_mul_f32_e32 v149, v149, v209
	v_mul_f32_e32 v150, v150, v209
	v_mul_f32_e32 v151, v151, v209
	v_cvt_pk_bf16_f32 v172, v144, v145
	v_cvt_pk_bf16_f32 v173, v146, v147
	v_cvt_pk_bf16_f32 v174, v148, v149
	v_cvt_pk_bf16_f32 v175, v150, v151
	v_mul_lo_u32 v160, s12, v198
	s_lshl_b32 s0, s13, 7
	v_add3_u32 v160, v160, v197, s0
	s_cmp_eq_u32 s14, 1
	s_cbranch_scc1 .Lrw_r0_qall
	s_cmp_eq_u32 s6, 0
	s_cbranch_scc1 .Lrw_r0_qall
	s_mov_b64 exec, s[26:27]
.Lrw_r0_qall:
	global_store_dwordx4 v160, v[172:175], s[50:51]
	s_mov_b64 exec, s[20:21]
	v_lshlrev_b32_e32 v144, 16, v16
	v_and_b32_e32 v145, 0xffff0000, v16
	v_lshlrev_b32_e32 v146, 16, v17
	v_and_b32_e32 v147, 0xffff0000, v17
	v_lshlrev_b32_e32 v148, 16, v18
	v_and_b32_e32 v149, 0xffff0000, v18
	v_lshlrev_b32_e32 v150, 16, v19
	v_and_b32_e32 v151, 0xffff0000, v19
	s_cmp_eq_u32 s14, 0
	s_cbranch_scc1 .Lrw_r0_nokr
	s_nop 0
	v_mov_b32_dpp v152, v144 quad_perm:[1,0,3,2] row_mask:0xf bank_mask:0xf
	v_mov_b32_dpp v153, v145 quad_perm:[1,0,3,2] row_mask:0xf bank_mask:0xf
	v_mov_b32_dpp v154, v146 quad_perm:[1,0,3,2] row_mask:0xf bank_mask:0xf
	v_mov_b32_dpp v155, v147 quad_perm:[1,0,3,2] row_mask:0xf bank_mask:0xf
	v_mov_b32_dpp v156, v148 quad_perm:[1,0,3,2] row_mask:0xf bank_mask:0xf
	v_mov_b32_dpp v157, v149 quad_perm:[1,0,3,2] row_mask:0xf bank_mask:0xf
	v_mov_b32_dpp v158, v150 quad_perm:[1,0,3,2] row_mask:0xf bank_mask:0xf
	v_mov_b32_dpp v159, v151 quad_perm:[1,0,3,2] row_mask:0xf bank_mask:0xf
	v_mul_f32_e32 v152, v152, v44
	v_mul_f32_e32 v144, v144, v36
	v_fmac_f32_e32 v144, v152, v208
	v_mul_f32_e32 v153, v153, v45
	v_mul_f32_e32 v145, v145, v37
	v_fmac_f32_e32 v145, v153, v208
	v_mul_f32_e32 v154, v154, v46
	v_mul_f32_e32 v146, v146, v38
	v_fmac_f32_e32 v146, v154, v208
	v_mul_f32_e32 v155, v155, v47
	v_mul_f32_e32 v147, v147, v39
	v_fmac_f32_e32 v147, v155, v208
	v_mul_f32_e32 v156, v156, v48
	v_mul_f32_e32 v148, v148, v40
	v_fmac_f32_e32 v148, v156, v208
	v_mul_f32_e32 v157, v157, v49
	v_mul_f32_e32 v149, v149, v41
	v_fmac_f32_e32 v149, v157, v208
	v_mul_f32_e32 v158, v158, v50
	v_mul_f32_e32 v150, v150, v42
	v_fmac_f32_e32 v150, v158, v208
	v_mul_f32_e32 v159, v159, v51
	v_mul_f32_e32 v151, v151, v43
	v_fmac_f32_e32 v151, v159, v208
.Lrw_r0_nokr:
	v_cvt_pk_bf16_f32 v172, v144, v145
	v_cvt_pk_bf16_f32 v173, v146, v147
	v_cvt_pk_bf16_f32 v174, v148, v149
	v_cvt_pk_bf16_f32 v175, v150, v151
	v_mul_lo_u32 v160, s12, v204
	s_mul_i32 s0, s13, 192
	v_add3_u32 v160, v160, v203, s0
	s_mov_b64 exec, s[78:79]
	global_store_dwordx4 v160, v[172:175], s[50:51]
	s_mov_b64 exec, s[20:21]
	s_nop 1
	s_mov_b32 s4, s18
	s_cmp_ge_u32 s4, 34816
	s_cbranch_scc1 .Lrw_done
	s_add_u32 s18, s4, s5
	s_min_u32 s17, s18, 34815
	s_mul_i32 s0, s17, 5184
	s_add_u32 s0, s0, 0x5cbd000
	s_add_u32 s10, s50, s0
	s_addc_u32 s11, s51, 0
	s_and_b32 s1, s17, 0xfff
	s_lshr_b32 s7, s1, 6
	s_and_b32 s19, s1, 63
	global_load_dwordx4 v[0:3], v196, s[10:11]
	global_load_dwordx4 v[4:7], v199, s[10:11]
	global_load_dwordx4 v[12:15], v200, s[10:11]
	global_load_dwordx4 v[16:19], v202, s[10:11]
	v_mov_b32_e32 v212, s19
	v_mov_b32_e32 v213, s7
	v_cndmask_b32_e64 v212, v212, v213, s[100:101]
	v_lshl_add_u32 v212, v212, 6, v205
	v_add_u32_e32 v213, 0x1000, v212
	global_load_dwordx4 v[20:23], v212, s[82:83]
	global_load_dwordx4 v[24:27], v212, s[82:83] offset:16
	global_load_dwordx4 v[28:31], v213, s[82:83]
	global_load_dwordx4 v[32:35], v213, s[82:83] offset:16
	v_mov_b32_e32 v212, s7
	v_mov_b32_e32 v213, s19
	v_cndmask_b32_e64 v212, v212, v213, s[70:71]
	v_lshlrev_b32_e32 v212, 5, v212
	global_load_dwordx4 v[36:39], v212, s[82:83]
	global_load_dwordx4 v[40:43], v212, s[82:83] offset:16
	global_load_dwordx4 v[44:47], v212, s[82:83] offset:2048
	global_load_dwordx4 v[48:51], v212, s[82:83] offset:2064
	s_lshr_b32 s12, s4, 12
	s_and_b32 s13, s4, 0xfff
	s_mov_b32 s14, 1
	s_cmp_lt_u32 s4, 0x8000
	s_cbranch_scc1 .Lrw_r1_lat
	s_sub_i32 s12, s4, 0x8000
	s_and_b32 s13, s12, 0xff
	s_add_i32 s13, s13, 0x1000
	s_lshr_b32 s12, s12, 8
	s_mov_b32 s14, 0
.Lrw_r1_lat:
	s_waitcnt vmcnt(16)
	v_lshlrev_b32_e32 v144, 16, v56
	v_and_b32_e32 v145, 0xffff0000, v56
	v_lshlrev_b32_e32 v146, 16, v57
	v_and_b32_e32 v147, 0xffff0000, v57
	v_lshlrev_b32_e32 v148, 16, v58
	v_and_b32_e32 v149, 0xffff0000, v58
	v_lshlrev_b32_e32 v150, 16, v59
	v_and_b32_e32 v151, 0xffff0000, v59
	v_mul_f32_e32 v160, v144, v144
	v_fmac_f32_e32 v160, v145, v145
	v_fmac_f32_e32 v160, v146, v146
	v_fmac_f32_e32 v160, v147, v147
	v_fmac_f32_e32 v160, v148, v148
	v_fmac_f32_e32 v160, v149, v149
	v_fmac_f32_e32 v160, v150, v150
	v_fmac_f32_e32 v160, v151, v151
	s_nop 1
	v_add_f32_dpp v160, v160, v160 quad_perm:[1,0,3,2] row_mask:0xf bank_mask:0xf
	s_nop 1
	v_add_f32_dpp v160, v160, v160 quad_perm:[2,3,0,1] row_mask:0xf bank_mask:0xf
	s_nop 1
	v_add_f32_dpp v160, v160, v160 row_half_mirror row_mask:0xf bank_mask:0xf
	s_nop 1
	v_add_f32_dpp v160, v160, v160 row_mirror row_mask:0xf bank_mask:0xf
	s_nop 1
	v_readlane_b32 s0, v160, 0
	v_readlane_b32 s1, v160, 16
	v_readlane_b32 s7, v160, 32
	v_mov_b32_e32 v161, s0
	v_add_f32_e32 v161, s1, v161
	v_mov_b32_e32 v162, 0x358637bd
	v_fmamk_f32 v161, v161, 0x3b800000, v162
	v_mov_b32_e32 v163, s7
	v_fmamk_f32 v163, v163, 0x3c000000, v162
	v_rsq_f32_e32 v214, v161
	v_rsq_f32_e32 v215, v163
	s_lshl_b32 s0, s4, 3
	v_mov_b32_e32 v164, s0
	s_mov_b64 exec, s[80:81]
	global_store_dwordx2 v164, v[214:215], s[98:99]
	s_mov_b64 exec, s[20:21]
	v_mul_lo_u32 v160, s12, v216
	s_lshl_b32 s0, s13, 7
	v_add3_u32 v160, v160, v201, s0
	s_mov_b64 exec, s[76:77]
	global_store_dwordx4 v160, v[60:63], s[50:51]
	s_mov_b64 exec, s[20:21]
	v_lshlrev_b32_e32 v144, 16, v52
	v_and_b32_e32 v145, 0xffff0000, v52
	v_lshlrev_b32_e32 v146, 16, v53
	v_and_b32_e32 v147, 0xffff0000, v53
	v_lshlrev_b32_e32 v148, 16, v54
	v_and_b32_e32 v149, 0xffff0000, v54
	v_lshlrev_b32_e32 v150, 16, v55
	v_and_b32_e32 v151, 0xffff0000, v55
	v_mul_f32_e32 v160, v144, v144
	v_fmac_f32_e32 v160, v145, v145
	v_fmac_f32_e32 v160, v146, v146
	v_fmac_f32_e32 v160, v147, v147
	v_fmac_f32_e32 v160, v148, v148
	v_fmac_f32_e32 v160, v149, v149
	v_fmac_f32_e32 v160, v150, v150
	v_fmac_f32_e32 v160, v151, v151
	s_nop 1
	v_add_f32_dpp v160, v160, v160 quad_perm:[1,0,3,2] row_mask:0xf bank_mask:0xf
	s_nop 1
	v_add_f32_dpp v160, v160, v160 quad_perm:[2,3,0,1] row_mask:0xf bank_mask:0xf
	s_nop 1
	v_add_f32_dpp v160, v160, v160 row_half_mirror row_mask:0xf bank_mask:0xf
	v_mov_b32_e32 v162, 0x358637bd
	v_fmamk_f32 v160, v160, 0x3c800000, v162
	v_rsq_f32_e32 v160, v160
	s_nop 0
	v_mul_f32_e32 v144, v144, v160
	v_mul_f32_e32 v144, v144, v188
	v_mul_f32_e32 v145, v145, v160
	v_mul_f32_e32 v145, v145, v189
	v_mul_f32_e32 v146, v146, v160
	v_mul_f32_e32 v146, v146, v190
	v_mul_f32_e32 v147, v147, v160
	v_mul_f32_e32 v147, v147, v191
	v_mul_f32_e32 v148, v148, v160
	v_mul_f32_e32 v148, v148, v192
	v_mul_f32_e32 v149, v149, v160
	v_mul_f32_e32 v149, v149, v193
	v_mul_f32_e32 v150, v150, v160
	v_mul_f32_e32 v150, v150, v194
	v_mul_f32_e32 v151, v151, v160
	v_mul_f32_e32 v151, v151, v195
	s_cmp_eq_u32 s14, 0
	s_cbranch_scc1 .Lrw_r1_norope
	s_nop 0
	v_mov_b32_dpp v152, v144 quad_perm:[2,3,0,1] row_mask:0xf bank_mask:0xf
	v_mov_b32_dpp v153, v145 quad_perm:[2,3,0,1] row_mask:0xf bank_mask:0xf
	v_mov_b32_dpp v154, v146 quad_perm:[2,3,0,1] row_mask:0xf bank_mask:0xf
	v_mov_b32_dpp v155, v147 quad_perm:[2,3,0,1] row_mask:0xf bank_mask:0xf
	v_mov_b32_dpp v156, v148 quad_perm:[2,3,0,1] row_mask:0xf bank_mask:0xf
	v_mov_b32_dpp v157, v149 quad_perm:[2,3,0,1] row_mask:0xf bank_mask:0xf
	v_mov_b32_dpp v158, v150 quad_perm:[2,3,0,1] row_mask:0xf bank_mask:0xf
	v_mov_b32_dpp v159, v151 quad_perm:[2,3,0,1] row_mask:0xf bank_mask:0xf
	v_mul_f32_e32 v152, v152, v104
	v_mul_f32_e32 v144, v144, v96
	v_fmac_f32_e32 v144, v152, v207
	v_mul_f32_e32 v153, v153, v105
	v_mul_f32_e32 v145, v145, v97
	v_fmac_f32_e32 v145, v153, v207
	v_mul_f32_e32 v154, v154, v106
	v_mul_f32_e32 v146, v146, v98
	v_fmac_f32_e32 v146, v154, v207
	v_mul_f32_e32 v155, v155, v107
	v_mul_f32_e32 v147, v147, v99
	v_fmac_f32_e32 v147, v155, v207
	v_mul_f32_e32 v156, v156, v108
	v_mul_f32_e32 v148, v148, v100
	v_fmac_f32_e32 v148, v156, v207
	v_mul_f32_e32 v157, v157, v109
	v_mul_f32_e32 v149, v149, v101
	v_fmac_f32_e32 v149, v157, v207
	v_mul_f32_e32 v158, v158, v110
	v_mul_f32_e32 v150, v150, v102
	v_fmac_f32_e32 v150, v158, v207
	v_mul_f32_e32 v159, v159, v111
	v_mul_f32_e32 v151, v151, v103
	v_fmac_f32_e32 v151, v159, v207

.Lrw_r1_qall:
	global_store_dwordx4 v160, v[172:175], s[50:51]
	s_mov_b64 exec, s[20:21]
	v_lshlrev_b32_e32 v144, 16, v64
	v_and_b32_e32 v145, 0xffff0000, v64
	v_lshlrev_b32_e32 v146, 16, v65
	v_and_b32_e32 v147, 0xffff0000, v65
	v_lshlrev_b32_e32 v148, 16, v66
	v_and_b32_e32 v149, 0xffff0000, v66
	v_lshlrev_b32_e32 v150, 16, v67
	v_and_b32_e32 v151, 0xffff0000, v67
	s_cmp_eq_u32 s14, 0
	s_cbranch_scc1 .Lrw_r1_nokr
	s_nop 0
	v_mov_b32_dpp v152, v144 quad_perm:[1,0,3,2] row_mask:0xf bank_mask:0xf
	v_mov_b32_dpp v153, v145 quad_perm:[1,0,3,2] row_mask:0xf bank_mask:0xf
	v_mov_b32_dpp v154, v146 quad_perm:[1,0,3,2] row_mask:0xf bank_mask:0xf
	v_mov_b32_dpp v155, v147 quad_perm:[1,0,3,2] row_mask:0xf bank_mask:0xf
	v_mov_b32_dpp v156, v148 quad_perm:[1,0,3,2] row_mask:0xf bank_mask:0xf
	v_mov_b32_dpp v157, v149 quad_perm:[1,0,3,2] row_mask:0xf bank_mask:0xf
	v_mov_b32_dpp v158, v150 quad_perm:[1,0,3,2] row_mask:0xf bank_mask:0xf
	v_mov_b32_dpp v159, v151 quad_perm:[1,0,3,2] row_mask:0xf bank_mask:0xf
	v_mul_f32_e32 v152, v152, v120
	v_mul_f32_e32 v144, v144, v112
	v_fmac_f32_e32 v144, v152, v208
	v_mul_f32_e32 v153, v153, v121
	v_mul_f32_e32 v145, v145, v113
	v_fmac_f32_e32 v145, v153, v208
	v_mul_f32_e32 v154, v154, v122
	v_mul_f32_e32 v146, v146, v114
	v_fmac_f32_e32 v146, v154, v208
	v_mul_f32_e32 v155, v155, v123
	v_mul_f32_e32 v147, v147, v115
	v_fmac_f32_e32 v147, v155, v208
	v_mul_f32_e32 v156, v156, v124
	v_mul_f32_e32 v148, v148, v116
	v_fmac_f32_e32 v148, v156, v208
	v_mul_f32_e32 v157, v157, v125
	v_mul_f32_e32 v149, v149, v117
	v_fmac_f32_e32 v149, v157, v208
	v_mul_f32_e32 v158, v158, v126
	v_mul_f32_e32 v150, v150, v118
	v_fmac_f32_e32 v150, v158, v208
	v_mul_f32_e32 v159, v159, v127
	v_mul_f32_e32 v151, v151, v119
	v_fmac_f32_e32 v151, v159, v208
.Lrw_r1_nokr:
	v_cvt_pk_bf16_f32 v172, v144, v145
	v_cvt_pk_bf16_f32 v173, v146, v147
	v_cvt_pk_bf16_f32 v174, v148, v149
	v_cvt_pk_bf16_f32 v175, v150, v151
	v_mul_lo_u32 v160, s12, v204
	s_mul_i32 s0, s13, 192
	v_add3_u32 v160, v160, v203, s0
	s_mov_b64 exec, s[78:79]
	global_store_dwordx4 v160, v[172:175], s[50:51]
	s_mov_b64 exec, s[20:21]
	s_nop 1
	s_mov_b32 s4, s18
	s_cmp_ge_u32 s4, 34816
	s_cbranch_scc1 .Lrw_done
	s_branch .Lrw_loop
.Lrw_done:
	s_waitcnt vmcnt(0)
	s_mov_b64 exec, s[20:21]
	s_mov_b64 s[68:69], exec
